# k37 + seam poll loops: s_sleep 1 replaced by s_nop 0 (tighter polling, shorter detection delay)
# speedup vs baseline: 1.0041x; 1.0017x over previous
.LBB0_213:
	global_load_dword v15, v16, s[10:11] sc1
	global_load_dword v0, v16, s[12:13] sc1
	global_load_dword v1, v16, s[14:15] sc1
	global_load_dword v2, v16, s[16:17] sc1
	global_load_dword v3, v16, s[18:19] sc1
	global_load_dword v4, v16, s[22:23] sc1
	global_load_dword v5, v16, s[24:25] sc1
	global_load_dword v6, v16, s[26:27] sc1
	global_load_dword v7, v16, s[28:29] sc1
	global_load_dword v8, v16, s[30:31] sc1
	global_load_dword v9, v16, s[34:35] sc1
	global_load_dword v10, v16, s[36:37] sc1
	global_load_dword v11, v16, s[38:39] sc1
	global_load_dword v12, v16, s[40:41] sc1
	global_load_dword v13, v16, s[42:43] sc1
	global_load_dword v14, v16, s[44:45] sc1
	s_mov_b64 s[46:47], -1
	s_mov_b64 s[48:49], -1
	s_waitcnt vmcnt(14)
	v_add_u32_e32 v17, v0, v15
	s_waitcnt vmcnt(13)
	v_add_u32_e32 v17, v17, v1
	s_waitcnt vmcnt(12)
	v_add_u32_e32 v17, v17, v2
	s_waitcnt vmcnt(11)
	v_add_u32_e32 v17, v17, v3
	s_waitcnt vmcnt(10)
	v_add_u32_e32 v17, v17, v4
	s_waitcnt vmcnt(9)
	v_add_u32_e32 v17, v17, v5
	s_waitcnt vmcnt(8)
	v_add_u32_e32 v17, v17, v6
	s_waitcnt vmcnt(7)
	v_add_u32_e32 v17, v17, v7
	s_waitcnt vmcnt(6)
	v_add_u32_e32 v17, v17, v8
	s_waitcnt vmcnt(5)
	v_add_u32_e32 v17, v17, v9
	s_waitcnt vmcnt(4)
	v_add_u32_e32 v17, v17, v10
	s_waitcnt vmcnt(3)
	v_add_u32_e32 v17, v17, v11
	s_waitcnt vmcnt(2)
	v_add_u32_e32 v17, v17, v12
	s_waitcnt vmcnt(1)
	v_add_u32_e32 v17, v17, v13
	s_waitcnt vmcnt(0)
	v_add_u32_e32 v17, v17, v14
	v_cmp_eq_u32_e32 vcc, s53, v17
	s_cbranch_vccnz .LBB0_212
	s_and_b32 s46, s54, 0xff
	s_cmp_eq_u32 s46, 0
	s_mov_b64 s[46:47], -1
	s_mov_b64 s[50:51], -1
	s_nop 0
	s_cbranch_scc1 .LBB0_217
	s_and_b64 vcc, exec, s[50:51]
	s_cbranch_vccz .LBB0_212

.LBB0_231:
	s_and_b32 s26, s3, 0xff
	s_mov_b64 s[24:25], -1
	s_cmp_lg_u32 s26, 0
	s_mov_b64 s[28:29], -1
	s_nop 0
	s_cbranch_scc0 .LBB0_234
	s_and_b64 vcc, exec, s[28:29]
	s_cbranch_vccz .LBB0_230

.LBB0_248:
	s_and_b32 s22, s3, 0xff
	s_cmp_lg_u32 s22, 0
	s_mov_b64 s[24:25], -1
	s_nop 0
	s_cbranch_scc0 .LBB0_251
	s_mov_b64 s[26:27], -1
	s_and_b64 vcc, exec, s[24:25]
	s_cbranch_vccz .LBB0_247

.LBB0_297:
	s_and_b32 s14, s22, 0xff
	s_mov_b64 s[12:13], -1
	s_cmp_lg_u32 s14, 0
	s_mov_b64 s[16:17], -1
	s_nop 0
	s_cbranch_scc0 .LBB0_300
	s_and_b64 vcc, exec, s[16:17]
	s_cbranch_vccz .LBB0_296

.LBB0_364:
	s_and_b32 s46, s26, 0xff
	s_mov_b64 s[42:43], -1
	s_cmp_lg_u32 s46, 0
	s_mov_b64 s[48:49], -1
	s_nop 0
	s_cbranch_scc0 .LBB0_367
	s_and_b64 vcc, exec, s[48:49]
	s_cbranch_vccz .LBB0_363

.LBB0_383:
	global_load_dword v16, v1, s[22:23] sc1
	global_load_dword v0, v1, s[46:47] sc1
	global_load_dword v2, v1, s[48:49] sc1
	global_load_dword v3, v1, s[50:51] sc1
	global_load_dword v4, v1, s[58:59] sc1
	global_load_dword v5, v1, s[42:43] sc1
	global_load_dword v6, v1, s[66:67] sc1
	global_load_dword v7, v1, s[68:69] sc1
	global_load_dword v8, v1, s[70:71] sc1
	global_load_dword v9, v1, s[40:41] sc1
	global_load_dword v10, v1, s[60:61] sc1
	global_load_dword v11, v1, s[24:25] sc1
	global_load_dword v12, v1, s[92:93] sc1
	global_load_dword v13, v1, s[78:79] sc1
	global_load_dword v14, v1, s[82:83] sc1
	global_load_dword v15, v1, s[84:85] sc1
	s_mov_b64 s[86:87], -1
	s_mov_b64 s[88:89], -1
	s_waitcnt vmcnt(14)
	v_add_u32_e32 v17, v0, v16
	s_waitcnt vmcnt(13)
	v_add_u32_e32 v17, v17, v2
	s_waitcnt vmcnt(12)
	v_add_u32_e32 v17, v17, v3
	s_waitcnt vmcnt(11)
	v_add_u32_e32 v17, v17, v4
	s_waitcnt vmcnt(10)
	v_add_u32_e32 v17, v17, v5
	s_waitcnt vmcnt(9)
	v_add_u32_e32 v17, v17, v6
	s_waitcnt vmcnt(8)
	v_add_u32_e32 v17, v17, v7
	s_waitcnt vmcnt(7)
	v_add_u32_e32 v17, v17, v8
	s_waitcnt vmcnt(6)
	v_add_u32_e32 v17, v17, v9
	s_waitcnt vmcnt(5)
	v_add_u32_e32 v17, v17, v10
	s_waitcnt vmcnt(4)
	v_add_u32_e32 v17, v17, v11
	s_waitcnt vmcnt(3)
	v_add_u32_e32 v17, v17, v12
	s_waitcnt vmcnt(2)
	v_add_u32_e32 v17, v17, v13
	s_waitcnt vmcnt(1)
	v_add_u32_e32 v17, v17, v14
	s_waitcnt vmcnt(0)
	v_add_u32_e32 v17, v17, v15
	v_cmp_eq_u32_e32 vcc, s65, v17
	s_cbranch_vccnz .LBB0_382
	s_and_b32 s74, s94, 0xff
	s_cmp_eq_u32 s74, 0
	s_mov_b64 s[74:75], -1
	s_nop 0
	s_cbranch_scc1 .LBB0_387
	s_and_b64 vcc, exec, s[74:75]
	s_cbranch_vccz .LBB0_382

.LBB0_401:
	s_and_b32 s58, s26, 0xff
	s_mov_b64 s[50:51], -1
	s_cmp_lg_u32 s58, 0
	s_mov_b64 s[60:61], -1
	s_nop 0
	s_cbranch_scc0 .LBB0_404
	s_and_b64 vcc, exec, s[60:61]
	s_cbranch_vccz .LBB0_400

.LBB0_418:
	s_and_b32 s50, s26, 0xff
	s_mov_b64 s[48:49], -1
	s_cmp_lg_u32 s50, 0
	s_mov_b64 s[58:59], -1
	s_nop 0
	s_cbranch_scc0 .LBB0_421
	s_and_b64 vcc, exec, s[58:59]
	s_cbranch_vccz .LBB0_417

.LBB0_654:
	s_and_b32 s5, s4, 0xff
	s_mov_b64 s[50:51], -1
	s_cmp_lg_u32 s5, 0
	s_mov_b64 s[60:61], -1
	s_nop 0
	s_cbranch_scc0 .LBB0_657
	s_and_b64 vcc, exec, s[60:61]
	s_cbranch_vccz .LBB0_653

.LBB0_683:
	global_load_dword v16, v1, s[50:51] sc1
	global_load_dword v0, v1, s[58:59] sc1
	global_load_dword v2, v1, s[94:95] sc1
	global_load_dword v3, v1, s[96:97] sc1
	global_load_dword v4, v1, s[42:43] sc1
	global_load_dword v5, v1, s[66:67] sc1
	global_load_dword v6, v1, s[68:69] sc1
	global_load_dword v7, v1, s[70:71] sc1
	global_load_dword v8, v1, s[40:41] sc1
	global_load_dword v9, v1, s[60:61] sc1
	global_load_dword v10, v1, s[24:25] sc1
	global_load_dword v11, v1, s[92:93] sc1
	global_load_dword v12, v1, s[78:79] sc1
	global_load_dword v13, v1, s[82:83] sc1
	global_load_dword v14, v1, s[84:85] sc1
	global_load_dword v15, v1, s[86:87] sc1
	s_mov_b64 s[88:89], -1
	s_mov_b64 s[74:75], -1
	s_waitcnt vmcnt(14)
	v_add_u32_e32 v17, v0, v16
	s_waitcnt vmcnt(13)
	v_add_u32_e32 v17, v17, v2
	s_waitcnt vmcnt(12)
	v_add_u32_e32 v17, v17, v3
	s_waitcnt vmcnt(11)
	v_add_u32_e32 v17, v17, v4
	s_waitcnt vmcnt(10)
	v_add_u32_e32 v17, v17, v5
	s_waitcnt vmcnt(9)
	v_add_u32_e32 v17, v17, v6
	s_waitcnt vmcnt(8)
	v_add_u32_e32 v17, v17, v7
	s_waitcnt vmcnt(7)
	v_add_u32_e32 v17, v17, v8
	s_waitcnt vmcnt(6)
	v_add_u32_e32 v17, v17, v9
	s_waitcnt vmcnt(5)
	v_add_u32_e32 v17, v17, v10
	s_waitcnt vmcnt(4)
	v_add_u32_e32 v17, v17, v11
	s_waitcnt vmcnt(3)
	v_add_u32_e32 v17, v17, v12
	s_waitcnt vmcnt(2)
	v_add_u32_e32 v17, v17, v13
	s_waitcnt vmcnt(1)
	v_add_u32_e32 v17, v17, v14
	s_waitcnt vmcnt(0)
	v_add_u32_e32 v17, v17, v15
	v_cmp_eq_u32_e32 vcc, s4, v17
	s_cbranch_vccnz .LBB0_682
	s_and_b32 s88, s5, 0xff
	s_cmp_eq_u32 s88, 0
	s_mov_b64 s[88:89], -1
	s_mov_b64 vcc, -1
	s_nop 0
	s_cbranch_scc1 .LBB0_687
	s_and_b64 vcc, exec, vcc
	s_cbranch_vccz .LBB0_682

.LBB0_701:
	s_and_b32 s5, s4, 0xff
	s_mov_b64 s[66:67], -1
	s_cmp_lg_u32 s5, 0
	s_mov_b64 s[70:71], -1
	s_nop 0
	s_cbranch_scc0 .LBB0_704
	s_and_b64 vcc, exec, s[70:71]
	s_cbranch_vccz .LBB0_700

.LBB0_718:
	s_and_b32 s5, s4, 0xff
	s_mov_b64 s[60:61], -1
	s_cmp_lg_u32 s5, 0
	s_mov_b64 s[68:69], -1
	s_nop 0
	s_cbranch_scc0 .LBB0_721
	s_and_b64 vcc, exec, s[68:69]
	s_cbranch_vccz .LBB0_717

.LBB0_895:
	s_and_b32 s5, s4, 0xff
	s_mov_b64 s[48:49], -1
	s_cmp_lg_u32 s5, 0
	s_mov_b64 s[58:59], -1
	s_nop 0
	s_cbranch_scc0 .LBB0_898
	s_and_b64 vcc, exec, s[58:59]
	s_cbranch_vccz .LBB0_894

.LBB0_1007:
	s_and_b32 s24, s26, 0xff
	s_mov_b64 s[22:23], -1
	s_cmp_lg_u32 s24, 0
	s_mov_b64 s[40:41], -1
	s_nop 0
	s_cbranch_scc0 .LBB0_1010
	s_and_b64 vcc, exec, s[40:41]
	s_cbranch_vccz .LBB0_1006

.LBB0_1027:
	global_load_dword v16, v1, s[12:13] sc1
	global_load_dword v0, v1, s[14:15] sc1
	global_load_dword v2, v1, s[16:17] sc1
	global_load_dword v3, v1, s[22:23] sc1
	global_load_dword v4, v1, s[42:43] sc1
	global_load_dword v5, v1, s[46:47] sc1
	global_load_dword v6, v1, s[48:49] sc1
	global_load_dword v7, v1, s[50:51] sc1
	global_load_dword v8, v1, s[40:41] sc1
	global_load_dword v9, v1, s[58:59] sc1
	global_load_dword v10, v1, s[24:25] sc1
	global_load_dword v11, v1, s[60:61] sc1
	global_load_dword v12, v1, s[66:67] sc1
	global_load_dword v13, v1, s[68:69] sc1
	global_load_dword v14, v1, s[70:71] sc1
	global_load_dword v15, v1, s[78:79] sc1
	s_mov_b64 s[82:83], -1
	s_mov_b64 s[74:75], -1
	s_waitcnt vmcnt(14)
	v_add_u32_e32 v17, v0, v16
	s_waitcnt vmcnt(13)
	v_add_u32_e32 v17, v17, v2
	s_waitcnt vmcnt(12)
	v_add_u32_e32 v17, v17, v3
	s_waitcnt vmcnt(11)
	v_add_u32_e32 v17, v17, v4
	s_waitcnt vmcnt(10)
	v_add_u32_e32 v17, v17, v5
	s_waitcnt vmcnt(9)
	v_add_u32_e32 v17, v17, v6
	s_waitcnt vmcnt(8)
	v_add_u32_e32 v17, v17, v7
	s_waitcnt vmcnt(7)
	v_add_u32_e32 v17, v17, v8
	s_waitcnt vmcnt(6)
	v_add_u32_e32 v17, v17, v9
	s_waitcnt vmcnt(5)
	v_add_u32_e32 v17, v17, v10
	s_waitcnt vmcnt(4)
	v_add_u32_e32 v17, v17, v11
	s_waitcnt vmcnt(3)
	v_add_u32_e32 v17, v17, v12
	s_waitcnt vmcnt(2)
	v_add_u32_e32 v17, v17, v13
	s_waitcnt vmcnt(1)
	v_add_u32_e32 v17, v17, v14
	s_waitcnt vmcnt(0)
	v_add_u32_e32 v17, v17, v15
	v_cmp_eq_u32_e32 vcc, s65, v17
	s_cbranch_vccnz .LBB0_1026
	s_and_b32 s82, s86, 0xff
	s_cmp_eq_u32 s82, 0
	s_mov_b64 s[82:83], -1
	s_mov_b64 s[84:85], -1
	s_nop 0
	s_cbranch_scc1 .LBB0_1031
	s_and_b64 vcc, exec, s[84:85]
	s_cbranch_vccz .LBB0_1026

.LBB0_1062:
	s_and_b32 s42, s26, 0xff
	s_mov_b64 s[40:41], -1
	s_cmp_lg_u32 s42, 0
	s_mov_b64 s[46:47], -1
	s_nop 0
	s_cbranch_scc0 .LBB0_1065
	s_and_b64 vcc, exec, s[46:47]
	s_cbranch_vccz .LBB0_1061

.LBB0_1227:
	s_and_b32 s16, s24, 0xff
	s_mov_b64 s[14:15], -1
	s_cmp_lg_u32 s16, 0
	s_mov_b64 s[22:23], -1
	s_nop 0
	s_cbranch_scc0 .LBB0_1230
	s_and_b64 vcc, exec, s[22:23]
	s_cbranch_vccz .LBB0_1226

.LBB0_1243:
	global_load_dword v16, v1, s[8:9] sc1
	global_load_dword v0, v1, s[10:11] sc1
	global_load_dword v2, v1, s[12:13] sc1
	global_load_dword v3, v1, s[14:15] sc1
	global_load_dword v4, v1, s[16:17] sc1
	global_load_dword v5, v1, s[22:23] sc1
	global_load_dword v6, v1, s[42:43] sc1
	global_load_dword v7, v1, s[46:47] sc1
	global_load_dword v8, v1, s[40:41] sc1
	global_load_dword v9, v1, s[48:49] sc1
	global_load_dword v10, v1, s[24:25] sc1
	global_load_dword v11, v1, s[50:51] sc1
	global_load_dword v12, v1, s[58:59] sc1
	global_load_dword v13, v1, s[60:61] sc1
	global_load_dword v14, v1, s[66:67] sc1
	global_load_dword v15, v1, s[68:69] sc1
	s_mov_b64 s[70:71], -1
	s_mov_b64 s[74:75], -1
	s_waitcnt vmcnt(14)
	v_add_u32_e32 v17, v0, v16
	s_waitcnt vmcnt(13)
	v_add_u32_e32 v17, v17, v2
	s_waitcnt vmcnt(12)
	v_add_u32_e32 v17, v17, v3
	s_waitcnt vmcnt(11)
	v_add_u32_e32 v17, v17, v4
	s_waitcnt vmcnt(10)
	v_add_u32_e32 v17, v17, v5
	s_waitcnt vmcnt(9)
	v_add_u32_e32 v17, v17, v6
	s_waitcnt vmcnt(8)
	v_add_u32_e32 v17, v17, v7
	s_waitcnt vmcnt(7)
	v_add_u32_e32 v17, v17, v8
	s_waitcnt vmcnt(6)
	v_add_u32_e32 v17, v17, v9
	s_waitcnt vmcnt(5)
	v_add_u32_e32 v17, v17, v10
	s_waitcnt vmcnt(4)
	v_add_u32_e32 v17, v17, v11
	s_waitcnt vmcnt(3)
	v_add_u32_e32 v17, v17, v12
	s_waitcnt vmcnt(2)
	v_add_u32_e32 v17, v17, v13
	s_waitcnt vmcnt(1)
	v_add_u32_e32 v17, v17, v14
	s_waitcnt vmcnt(0)
	v_add_u32_e32 v17, v17, v15
	v_cmp_eq_u32_e32 vcc, s64, v17
	s_cbranch_vccnz .LBB0_1242
	s_and_b32 s70, s65, 0xff
	s_cmp_eq_u32 s70, 0
	s_mov_b64 s[70:71], -1
	s_mov_b64 s[78:79], -1
	s_nop 0
	s_cbranch_scc1 .LBB0_1247
	s_and_b64 vcc, exec, s[78:79]
	s_cbranch_vccz .LBB0_1242

.LBB0_1261:
	s_and_b32 s37, s26, 0xff
	s_mov_b64 s[24:25], -1
	s_cmp_lg_u32 s37, 0
	s_mov_b64 s[42:43], -1
	s_nop 0
	s_cbranch_scc0 .LBB0_1264
	s_and_b64 vcc, exec, s[42:43]
	s_cbranch_vccz .LBB0_1260

.LBB0_1517:
	global_load_dword v16, v1, s[12:13] sc1
	global_load_dword v0, v1, s[14:15] sc1
	global_load_dword v2, v1, s[16:17] sc1
	global_load_dword v3, v1, s[22:23] sc1
	global_load_dword v4, v1, s[42:43] sc1
	global_load_dword v5, v1, s[46:47] sc1
	global_load_dword v6, v1, s[48:49] sc1
	global_load_dword v7, v1, s[50:51] sc1
	global_load_dword v8, v1, s[40:41] sc1
	global_load_dword v9, v1, s[58:59] sc1
	global_load_dword v10, v1, s[24:25] sc1
	global_load_dword v11, v1, s[60:61] sc1
	global_load_dword v12, v1, s[66:67] sc1
	global_load_dword v13, v1, s[68:69] sc1
	global_load_dword v14, v1, s[70:71] sc1
	global_load_dword v15, v1, s[78:79] sc1
	s_mov_b64 s[82:83], -1
	s_mov_b64 s[74:75], -1
	s_waitcnt vmcnt(14)
	v_add_u32_e32 v17, v0, v16
	s_waitcnt vmcnt(13)
	v_add_u32_e32 v17, v17, v2
	s_waitcnt vmcnt(12)
	v_add_u32_e32 v17, v17, v3
	s_waitcnt vmcnt(11)
	v_add_u32_e32 v17, v17, v4
	s_waitcnt vmcnt(10)
	v_add_u32_e32 v17, v17, v5
	s_waitcnt vmcnt(9)
	v_add_u32_e32 v17, v17, v6
	s_waitcnt vmcnt(8)
	v_add_u32_e32 v17, v17, v7
	s_waitcnt vmcnt(7)
	v_add_u32_e32 v17, v17, v8
	s_waitcnt vmcnt(6)
	v_add_u32_e32 v17, v17, v9
	s_waitcnt vmcnt(5)
	v_add_u32_e32 v17, v17, v10
	s_waitcnt vmcnt(4)
	v_add_u32_e32 v17, v17, v11
	s_waitcnt vmcnt(3)
	v_add_u32_e32 v17, v17, v12
	s_waitcnt vmcnt(2)
	v_add_u32_e32 v17, v17, v13
	s_waitcnt vmcnt(1)
	v_add_u32_e32 v17, v17, v14
	s_waitcnt vmcnt(0)
	v_add_u32_e32 v17, v17, v15
	v_cmp_eq_u32_e32 vcc, s77, v17
	s_cbranch_vccnz .LBB0_1516
	s_and_b32 s82, s86, 0xff
	s_cmp_eq_u32 s82, 0
	s_mov_b64 s[82:83], -1
	s_mov_b64 s[84:85], -1
	s_nop 0
	s_cbranch_scc1 .LBB0_1521
	s_and_b64 vcc, exec, s[84:85]
	s_cbranch_vccz .LBB0_1516

.LBB0_1732:
	s_and_b32 s40, s26, 0xff
	s_mov_b64 s[24:25], -1
	s_cmp_lg_u32 s40, 0
	s_mov_b64 s[42:43], -1
	s_nop 0
	s_cbranch_scc0 .LBB0_1735
	s_and_b64 vcc, exec, s[42:43]
	s_cbranch_vccz .LBB0_1731

.LBB0_1751:
	global_load_dword v16, v1, s[14:15] sc1
	global_load_dword v0, v1, s[16:17] sc1
	global_load_dword v2, v1, s[22:23] sc1
	global_load_dword v3, v1, s[46:47] sc1
	global_load_dword v4, v1, s[42:43] sc1
	global_load_dword v5, v1, s[48:49] sc1
	global_load_dword v6, v1, s[50:51] sc1
	global_load_dword v7, v1, s[58:59] sc1
	global_load_dword v8, v1, s[40:41] sc1
	global_load_dword v9, v1, s[60:61] sc1
	global_load_dword v10, v1, s[24:25] sc1
	global_load_dword v11, v1, s[66:67] sc1
	global_load_dword v12, v1, s[68:69] sc1
	global_load_dword v13, v1, s[70:71] sc1
	global_load_dword v14, v1, s[78:79] sc1
	global_load_dword v15, v1, s[82:83] sc1
	s_mov_b64 s[84:85], -1
	s_mov_b64 s[74:75], -1
	s_waitcnt vmcnt(14)
	v_add_u32_e32 v17, v0, v16
	s_waitcnt vmcnt(13)
	v_add_u32_e32 v17, v17, v2
	s_waitcnt vmcnt(12)
	v_add_u32_e32 v17, v17, v3
	s_waitcnt vmcnt(11)
	v_add_u32_e32 v17, v17, v4
	s_waitcnt vmcnt(10)
	v_add_u32_e32 v17, v17, v5
	s_waitcnt vmcnt(9)
	v_add_u32_e32 v17, v17, v6
	s_waitcnt vmcnt(8)
	v_add_u32_e32 v17, v17, v7
	s_waitcnt vmcnt(7)
	v_add_u32_e32 v17, v17, v8
	s_waitcnt vmcnt(6)
	v_add_u32_e32 v17, v17, v9
	s_waitcnt vmcnt(5)
	v_add_u32_e32 v17, v17, v10
	s_waitcnt vmcnt(4)
	v_add_u32_e32 v17, v17, v11
	s_waitcnt vmcnt(3)
	v_add_u32_e32 v17, v17, v12
	s_waitcnt vmcnt(2)
	v_add_u32_e32 v17, v17, v13
	s_waitcnt vmcnt(1)
	v_add_u32_e32 v17, v17, v14
	s_waitcnt vmcnt(0)
	v_add_u32_e32 v17, v17, v15
	v_cmp_eq_u32_e32 vcc, s65, v17
	s_cbranch_vccnz .LBB0_1750
	s_and_b32 s84, s88, 0xff
	s_cmp_eq_u32 s84, 0
	s_mov_b64 s[84:85], -1
	s_mov_b64 s[86:87], -1
	s_nop 0
	s_cbranch_scc1 .LBB0_1755
	s_and_b64 vcc, exec, s[86:87]
	s_cbranch_vccz .LBB0_1750

.LBB0_1769:
	s_and_b32 s48, s26, 0xff
	s_mov_b64 s[46:47], -1
	s_cmp_lg_u32 s48, 0
	s_mov_b64 s[50:51], -1
	s_nop 0
	s_cbranch_scc0 .LBB0_1772
	s_and_b64 vcc, exec, s[50:51]
	s_cbranch_vccz .LBB0_1768

.LBB0_2008:
	global_load_dword v16, v1, s[8:9] sc1
	global_load_dword v0, v1, s[10:11] sc1
	global_load_dword v2, v1, s[12:13] sc1
	global_load_dword v3, v1, s[14:15] sc1
	global_load_dword v4, v1, s[16:17] sc1
	global_load_dword v5, v1, s[22:23] sc1
	global_load_dword v6, v1, s[28:29] sc1
	global_load_dword v7, v1, s[42:43] sc1
	global_load_dword v8, v1, s[40:41] sc1
	global_load_dword v9, v1, s[46:47] sc1
	global_load_dword v10, v1, s[24:25] sc1
	global_load_dword v11, v1, s[48:49] sc1
	global_load_dword v12, v1, s[50:51] sc1
	global_load_dword v13, v1, s[58:59] sc1
	global_load_dword v14, v1, s[60:61] sc1
	global_load_dword v15, v1, s[66:67] sc1
	s_mov_b64 s[68:69], -1
	s_mov_b64 s[70:71], -1
	s_waitcnt vmcnt(14)
	v_add_u32_e32 v17, v0, v16
	s_waitcnt vmcnt(13)
	v_add_u32_e32 v17, v17, v2
	s_waitcnt vmcnt(12)
	v_add_u32_e32 v17, v17, v3
	s_waitcnt vmcnt(11)
	v_add_u32_e32 v17, v17, v4
	s_waitcnt vmcnt(10)
	v_add_u32_e32 v17, v17, v5
	s_waitcnt vmcnt(9)
	v_add_u32_e32 v17, v17, v6
	s_waitcnt vmcnt(8)
	v_add_u32_e32 v17, v17, v7
	s_waitcnt vmcnt(7)
	v_add_u32_e32 v17, v17, v8
	s_waitcnt vmcnt(6)
	v_add_u32_e32 v17, v17, v9
	s_waitcnt vmcnt(5)
	v_add_u32_e32 v17, v17, v10
	s_waitcnt vmcnt(4)
	v_add_u32_e32 v17, v17, v11
	s_waitcnt vmcnt(3)
	v_add_u32_e32 v17, v17, v12
	s_waitcnt vmcnt(2)
	v_add_u32_e32 v17, v17, v13
	s_waitcnt vmcnt(1)
	v_add_u32_e32 v17, v17, v14
	s_waitcnt vmcnt(0)
	v_add_u32_e32 v17, v17, v15
	v_cmp_eq_u32_e32 vcc, s64, v17
	s_cbranch_vccnz .LBB0_2007
	s_and_b32 s68, s65, 0xff
	s_cmp_eq_u32 s68, 0
	s_mov_b64 s[68:69], -1
	s_mov_b64 s[74:75], -1
	s_nop 0
	s_cbranch_scc1 .LBB0_2012
	s_and_b64 vcc, exec, s[74:75]
	s_cbranch_vccz .LBB0_2007

.LBB0_2026:
	s_and_b32 s28, s26, 0xff
	s_mov_b64 s[24:25], -1
	s_cmp_lg_u32 s28, 0
	s_mov_b64 s[40:41], -1
	s_nop 0
	s_cbranch_scc0 .LBB0_2029
	s_and_b64 vcc, exec, s[40:41]
	s_cbranch_vccz .LBB0_2025

.LBB0_2043:
	s_and_b32 s24, s26, 0xff
	s_mov_b64 s[22:23], -1
	s_cmp_lg_u32 s24, 0
	s_mov_b64 s[28:29], -1
	s_nop 0
	s_cbranch_scc0 .LBB0_2046
	s_and_b64 vcc, exec, s[28:29]
	s_cbranch_vccz .LBB0_2042

.LBB0_2064:
	s_and_b32 s16, s22, 0xff
	s_mov_b64 s[14:15], -1
	s_cmp_lg_u32 s16, 0
	s_mov_b64 s[18:19], -1
	s_nop 0
	s_cbranch_scc0 .LBB0_2067
	s_and_b64 vcc, exec, s[18:19]
	s_cbranch_vccz .LBB0_2063

.LBB0_2080:
	global_load_dword v15, v16, s[8:9] sc1
	global_load_dword v0, v16, s[10:11] sc1
	global_load_dword v1, v16, s[12:13] sc1
	global_load_dword v2, v16, s[14:15] sc1
	global_load_dword v3, v16, s[16:17] sc1
	global_load_dword v4, v16, s[18:19] sc1
	global_load_dword v5, v16, s[22:23] sc1
	global_load_dword v6, v16, s[24:25] sc1
	global_load_dword v7, v16, s[26:27] sc1
	global_load_dword v8, v16, s[28:29] sc1
	global_load_dword v9, v16, s[30:31] sc1
	global_load_dword v10, v16, s[34:35] sc1
	global_load_dword v11, v16, s[36:37] sc1
	global_load_dword v12, v16, s[38:39] sc1
	global_load_dword v13, v16, s[40:41] sc1
	global_load_dword v14, v16, s[42:43] sc1
	s_mov_b64 s[44:45], -1
	s_mov_b64 s[46:47], -1
	s_waitcnt vmcnt(14)
	v_add_u32_e32 v17, v0, v15
	s_waitcnt vmcnt(13)
	v_add_u32_e32 v17, v17, v1
	s_waitcnt vmcnt(12)
	v_add_u32_e32 v17, v17, v2
	s_waitcnt vmcnt(11)
	v_add_u32_e32 v17, v17, v3
	s_waitcnt vmcnt(10)
	v_add_u32_e32 v17, v17, v4
	s_waitcnt vmcnt(9)
	v_add_u32_e32 v17, v17, v5
	s_waitcnt vmcnt(8)
	v_add_u32_e32 v17, v17, v6
	s_waitcnt vmcnt(7)
	v_add_u32_e32 v17, v17, v7
	s_waitcnt vmcnt(6)
	v_add_u32_e32 v17, v17, v8
	s_waitcnt vmcnt(5)
	v_add_u32_e32 v17, v17, v9
	s_waitcnt vmcnt(4)
	v_add_u32_e32 v17, v17, v10
	s_waitcnt vmcnt(3)
	v_add_u32_e32 v17, v17, v11
	s_waitcnt vmcnt(2)
	v_add_u32_e32 v17, v17, v12
	s_waitcnt vmcnt(1)
	v_add_u32_e32 v17, v17, v13
	s_waitcnt vmcnt(0)
	v_add_u32_e32 v17, v17, v14
	v_cmp_eq_u32_e32 vcc, s52, v17
	s_cbranch_vccnz .LBB0_2079
	s_and_b32 s44, s53, 0xff
	s_cmp_eq_u32 s44, 0
	s_mov_b64 s[44:45], -1
	s_mov_b64 s[48:49], -1
	s_nop 0
	s_cbranch_scc1 .LBB0_2084
	s_and_b64 vcc, exec, s[48:49]
	s_cbranch_vccz .LBB0_2079

.LBB0_2098:
	s_and_b32 s24, s28, 0xff
	s_mov_b64 s[22:23], -1
	s_cmp_lg_u32 s24, 0
	s_mov_b64 s[26:27], -1
	s_nop 0
	s_cbranch_scc0 .LBB0_2101
	s_and_b64 vcc, exec, s[26:27]
	s_cbranch_vccz .LBB0_2097

.LBB0_2115:
	s_and_b32 s18, s26, 0xff
	s_cmp_lg_u32 s18, 0
	s_mov_b64 s[22:23], -1
	s_nop 0
	s_cbranch_scc0 .LBB0_2118
	s_mov_b64 s[24:25], -1
	s_and_b64 vcc, exec, s[22:23]
	s_cbranch_vccz .LBB0_2114
